# GLA pass B: per-row O-tile LDS updates batched (no per-element branch / serialized LDS round trips)
# speedup vs baseline: 1.0056x; 1.0014x over previous
.LBB0_623:
	s_or_b64 exec, exec, s[92:93]
	v_mov_b32_e32 v0, v202
	v_mov_b32_e32 v61, v202
	v_and_b32_e32 v2, 31, v0
	v_mul_u32_u24_e32 v2, 0x48, v2
	v_lshrrev_b32_e32 v0, 1, v0
	v_lshlrev_b32_e32 v6, 1, v2
	v_and_b32_e32 v0, 16, v0
	v_add3_u32 v60, v89, v6, v0
	ds_read_b128 v[2:5], v60 offset:33792
	v_add3_u32 v0, v90, v6, v0
	ds_read_b128 v[6:9], v0
	ds_read_b128 v[142:145], v60 offset:33824
	ds_read_b128 v[146:149], v0 offset:32
	ds_read_b128 v[150:153], v60 offset:33856
	s_andn2_b64 vcc, exec, s[96:97]
	s_waitcnt lgkmcnt(3)
	v_mfma_f32_32x32x16_bf16 v[2:17], v[2:5], v[6:9], 0
	s_waitcnt lgkmcnt(1)
	v_mfma_f32_32x32x16_bf16 v[2:17], v[142:145], v[146:149], v[2:17]
	ds_read_b128 v[142:145], v60 offset:33888
	ds_read_b128 v[146:149], v0 offset:64
	ds_read_b128 v[154:157], v0 offset:96
	s_waitcnt lgkmcnt(0)
	s_barrier
	s_nop 0
	v_and_b32_e32 v0, 31, v61
	v_mfma_f32_32x32x16_bf16 v[2:17], v[150:153], v[146:149], v[2:17]
	v_lshrrev_b32_e32 v60, 1, v61
	v_mul_u32_u24_e32 v0, 0x48, v0
	v_and_b32_e32 v60, 16, v60
	v_lshlrev_b32_e32 v0, 1, v0
	v_add3_u32 v61, v89, v0, v60
	v_add3_u32 v0, v91, v0, v60
	v_cndmask_b32_e64 v60, 0, 1, s[96:97]
	v_mfma_f32_32x32x16_bf16 v[2:17], v[142:145], v[154:157], v[2:17]
	ds_read_b128 v[142:145], v61 offset:52224
	ds_read_b128 v[146:149], v0 offset:61440
	ds_read_b128 v[150:153], v61 offset:52256
	ds_read_b128 v[154:157], v0 offset:61472
	s_waitcnt lgkmcnt(2)
	v_mfma_f32_32x32x16_bf16 v[2:17], v[142:145], v[146:149], v[2:17]
	s_waitcnt lgkmcnt(0)
	v_mfma_f32_32x32x16_bf16 v[2:17], v[150:153], v[154:157], v[2:17]
	ds_read_b128 v[142:145], v61 offset:52288
	ds_read_b128 v[146:149], v0 offset:61504
	ds_read_b128 v[150:153], v61 offset:52320
	ds_read_b128 v[154:157], v0 offset:61536
	v_cmp_ne_u32_e64 s[74:75], 1, v60
	s_waitcnt lgkmcnt(2)
	v_mfma_f32_32x32x16_bf16 v[2:17], v[142:145], v[146:149], v[2:17]
	s_waitcnt lgkmcnt(0)
	v_mfma_f32_32x32x16_bf16 v[2:17], v[150:153], v[154:157], v[2:17]
	v_cndmask_b32_e64 v142, v110, v92, s[74:75]
	v_cndmask_b32_e64 v143, v112, v111, s[74:75]
	v_cndmask_b32_e64 v144, v114, v113, s[74:75]
	v_cndmask_b32_e64 v145, v116, v115, s[74:75]
	v_cndmask_b32_e64 v146, v118, v117, s[74:75]
	v_cndmask_b32_e64 v147, v120, v119, s[74:75]
	v_cndmask_b32_e64 v148, v122, v121, s[74:75]
	v_cndmask_b32_e64 v149, v124, v123, s[74:75]
	v_mad_u32_u24 v142, v142, s29, v93
	v_mad_u32_u24 v143, v143, s29, v93
	v_mad_u32_u24 v144, v144, s29, v93
	v_mad_u32_u24 v145, v145, s29, v93
	v_mad_u32_u24 v146, v146, s29, v93
	v_mad_u32_u24 v147, v147, s29, v93
	v_mad_u32_u24 v148, v148, s29, v93
	v_mad_u32_u24 v149, v149, s29, v93
	v_cndmask_b32_e64 v150, v126, v125, s[74:75]
	v_cndmask_b32_e64 v151, v128, v127, s[74:75]
	v_cndmask_b32_e64 v152, v130, v129, s[74:75]
	v_cndmask_b32_e64 v153, v132, v131, s[74:75]
	v_cndmask_b32_e64 v154, v134, v133, s[74:75]
	v_cndmask_b32_e64 v155, v136, v135, s[74:75]
	v_cndmask_b32_e64 v156, v138, v137, s[74:75]
	v_cndmask_b32_e64 v157, v140, v139, s[74:75]
	v_mad_u32_u24 v150, v150, s29, v93
	v_mad_u32_u24 v151, v151, s29, v93
	v_mad_u32_u24 v152, v152, s29, v93
	v_mad_u32_u24 v153, v153, s29, v93
	v_mad_u32_u24 v154, v154, s29, v93
	v_mad_u32_u24 v155, v155, s29, v93
	v_mad_u32_u24 v156, v156, s29, v93
	v_mad_u32_u24 v157, v157, s29, v93
	s_and_b64 vcc, exec, s[74:75]
	s_cbranch_vccz .Lpb_oacc
	ds_write_b32 v142, v2
	ds_write_b32 v143, v3
	ds_write_b32 v144, v4
	ds_write_b32 v145, v5
	ds_write_b32 v146, v6
	ds_write_b32 v147, v7
	ds_write_b32 v148, v8
	ds_write_b32 v149, v9
	ds_write_b32 v150, v10
	ds_write_b32 v151, v11
	ds_write_b32 v152, v12
	ds_write_b32 v153, v13
	ds_write_b32 v154, v14
	ds_write_b32 v155, v15
	ds_write_b32 v156, v16
	v_mov_b32_e32 v0, v157
	s_branch .LBB0_601
.Lpb_oacc:
	ds_read_b32 v158, v142
	ds_read_b32 v159, v143
	ds_read_b32 v160, v144
	ds_read_b32 v161, v145
	s_waitcnt lgkmcnt(0)
	v_add_f32_e32 v2, v2, v158
	v_add_f32_e32 v3, v3, v159
	v_add_f32_e32 v4, v4, v160
	v_add_f32_e32 v5, v5, v161
	ds_write_b32 v142, v2
	ds_write_b32 v143, v3
	ds_write_b32 v144, v4
	ds_write_b32 v145, v5
	ds_read_b32 v158, v146
	ds_read_b32 v159, v147
	ds_read_b32 v160, v148
	ds_read_b32 v161, v149
	s_waitcnt lgkmcnt(0)
	v_add_f32_e32 v6, v6, v158
	v_add_f32_e32 v7, v7, v159
	v_add_f32_e32 v8, v8, v160
	v_add_f32_e32 v9, v9, v161
	ds_write_b32 v146, v6
	ds_write_b32 v147, v7
	ds_write_b32 v148, v8
	ds_write_b32 v149, v9
	ds_read_b32 v158, v150
	ds_read_b32 v159, v151
	ds_read_b32 v160, v152
	ds_read_b32 v161, v153
	s_waitcnt lgkmcnt(0)
	v_add_f32_e32 v10, v10, v158
	v_add_f32_e32 v11, v11, v159
	v_add_f32_e32 v12, v12, v160
	v_add_f32_e32 v13, v13, v161
	ds_write_b32 v150, v10
	ds_write_b32 v151, v11
	ds_write_b32 v152, v12
	ds_write_b32 v153, v13
	ds_read_b32 v158, v154
	ds_read_b32 v159, v155
	ds_read_b32 v160, v156
	ds_read_b32 v161, v157
	s_waitcnt lgkmcnt(0)
	v_add_f32_e32 v14, v14, v158
	v_add_f32_e32 v15, v15, v159
	v_add_f32_e32 v16, v16, v160
	v_add_f32_e32 v17, v17, v161
	ds_write_b32 v154, v14
	ds_write_b32 v155, v15
	ds_write_b32 v156, v16
	v_mov_b32_e32 v0, v157
	s_branch .LBB0_601
